# row-norm phases: each XCD normalises the rows of its own row tiles (the rows its GEMM blocks produce and consume)
# speedup vs baseline: 1.0061x; 1.0061x over previous
.LBB0_144:
	s_andn2_b64 vcc, exec, s[0:1]
	s_cbranch_vccnz .LBB0_199
	s_mov_b64 s[2:3], s[84:85]
	v_mov_b32_e32 v0, v196
	v_mov_b32_e32 v2, v196
	v_readlane_b32 s0, v249, 1
	s_nop 0
	s_cmpk_lg_u32 s0, 0x200
	s_cbranch_scc1 .Lnrm_mix_orig
	v_readlane_b32 s0, v249, 5
	v_lshrrev_b32_e32 v68, 6, v196
	s_load_dwordx4 s[28:31], s[84:85], 0x130
	s_load_dwordx2 s[32:33], s[84:85], 0x48
	v_and_b32_e32 v69, 63, v196
	v_readfirstlane_b32 s1, v68
	v_lshlrev_b32_e32 v70, 4, v69
	v_lshlrev_b32_e32 v71, 3, v69
	s_add_i32 s0, s0, s1
	s_lshr_b32 s2, s0, 2
	s_and_b32 s3, s2, 7
	s_lshr_b32 s2, s2, 3
	s_lshl_b32 s2, s2, 2
	s_add_i32 s2, s2, s1
	s_lshl_b32 s0, s3, 7
	s_and_b32 s3, s2, 0x7f
	s_add_i32 s0, s0, s3
	s_lshr_b32 s2, s2, 7
	s_lshl_b32 s2, s2, 10
	s_add_i32 s0, s0, s2
	s_waitcnt lgkmcnt(0)
	s_add_u32 s32, s32, 0x1000
	s_addc_u32 s33, s33, 0
	global_load_dwordx4 v[4:7], v70, s[32:33]
	global_load_dwordx4 v[8:11], v70, s[32:33] offset:1024
	global_load_dwordx4 v[12:15], v70, s[32:33] offset:2048
	global_load_dwordx4 v[16:19], v70, s[32:33] offset:3072
	s_lshl_b32 s2, s0, 12
	s_add_u32 s34, s28, s2
	s_addc_u32 s35, s29, 0
	s_lshl_b32 s2, s0, 11
	s_add_u32 s36, s30, s2
	s_addc_u32 s37, s31, 0
	global_load_dwordx4 v[20:23], v70, s[34:35]
	global_load_dwordx4 v[24:27], v70, s[34:35] offset:1024
	global_load_dwordx4 v[28:31], v70, s[34:35] offset:2048
	global_load_dwordx4 v[32:35], v70, s[34:35] offset:3072
	s_add_u32 s34, s34, 0x800000
	s_addc_u32 s35, s35, 0
	global_load_dwordx4 v[36:39], v70, s[34:35]
	global_load_dwordx4 v[40:43], v70, s[34:35] offset:1024
	global_load_dwordx4 v[44:47], v70, s[34:35] offset:2048
	global_load_dwordx4 v[48:51], v70, s[34:35] offset:3072
	s_add_u32 s34, s34, 0x800000
	s_addc_u32 s35, s35, 0
	global_load_dwordx4 v[52:55], v70, s[34:35]
	global_load_dwordx4 v[56:59], v70, s[34:35] offset:1024
	global_load_dwordx4 v[60:63], v70, s[34:35] offset:2048
	global_load_dwordx4 v[64:67], v70, s[34:35] offset:3072
	s_add_u32 s34, s34, 0x800000
	s_addc_u32 s35, s35, 0
	s_waitcnt vmcnt(8)
	v_mul_f32_e32 v72, v20, v20
	v_mul_f32_e32 v73, v21, v21
	v_fmac_f32_e32 v72, v22, v22
	v_fmac_f32_e32 v73, v23, v23
	v_fmac_f32_e32 v72, v24, v24
	v_fmac_f32_e32 v73, v25, v25
	v_fmac_f32_e32 v72, v26, v26
	v_fmac_f32_e32 v73, v27, v27
	v_fmac_f32_e32 v72, v28, v28
	v_fmac_f32_e32 v73, v29, v29
	v_fmac_f32_e32 v72, v30, v30
	v_fmac_f32_e32 v73, v31, v31
	v_fmac_f32_e32 v72, v32, v32
	v_fmac_f32_e32 v73, v33, v33
	v_fmac_f32_e32 v72, v34, v34
	v_fmac_f32_e32 v73, v35, v35
	v_add_f32_e32 v72, v72, v73
	s_nop 1
	v_add_f32_dpp v72, v72, v72 quad_perm:[1,0,3,2] row_mask:0xf bank_mask:0xf
	s_nop 1
	v_add_f32_dpp v72, v72, v72 quad_perm:[2,3,0,1] row_mask:0xf bank_mask:0xf
	s_nop 1
	v_add_f32_dpp v72, v72, v72 row_half_mirror row_mask:0xf bank_mask:0xf
	s_nop 1
	v_add_f32_dpp v72, v72, v72 row_mirror row_mask:0xf bank_mask:0xf
	s_nop 1
	v_add_f32_dpp v72, v72, v72 row_bcast:15 row_mask:0xa bank_mask:0xf
	s_nop 1
	v_add_f32_dpp v72, v72, v72 row_bcast:31 row_mask:0xc bank_mask:0xf
	s_nop 1
	v_readlane_b32 s3, v72, 63
	s_nop 1
	v_mov_b32_e32 v72, s3
	v_fmamk_f32 v72, v72, 0x3a800000, v172
	v_rsq_f32_e32 v72, v72
	s_nop 0
	v_mul_f32_e32 v20, v20, v72
	v_mul_f32_e32 v21, v21, v72
	v_mul_f32_e32 v22, v22, v72
	v_mul_f32_e32 v23, v23, v72
	v_mul_f32_e32 v20, v4, v20
	v_mul_f32_e32 v21, v5, v21
	v_mul_f32_e32 v22, v6, v22
	v_mul_f32_e32 v23, v7, v23
	v_cvt_pk_bf16_f32 v74, v20, v21
	v_cvt_pk_bf16_f32 v75, v22, v23
	global_store_dwordx2 v71, v[74:75], s[36:37]
	v_mul_f32_e32 v24, v24, v72
	v_mul_f32_e32 v25, v25, v72
	v_mul_f32_e32 v26, v26, v72
	v_mul_f32_e32 v27, v27, v72
	v_mul_f32_e32 v24, v8, v24
	v_mul_f32_e32 v25, v9, v25
	v_mul_f32_e32 v26, v10, v26
	v_mul_f32_e32 v27, v11, v27
	v_cvt_pk_bf16_f32 v76, v24, v25
	v_cvt_pk_bf16_f32 v77, v26, v27
	global_store_dwordx2 v71, v[76:77], s[36:37] offset:512
	v_mul_f32_e32 v28, v28, v72
	v_mul_f32_e32 v29, v29, v72
	v_mul_f32_e32 v30, v30, v72
	v_mul_f32_e32 v31, v31, v72
	v_mul_f32_e32 v28, v12, v28
	v_mul_f32_e32 v29, v13, v29
	v_mul_f32_e32 v30, v14, v30
	v_mul_f32_e32 v31, v15, v31
	v_cvt_pk_bf16_f32 v78, v28, v29
	v_cvt_pk_bf16_f32 v79, v30, v31
	global_store_dwordx2 v71, v[78:79], s[36:37] offset:1024
	v_mul_f32_e32 v32, v32, v72
	v_mul_f32_e32 v33, v33, v72
	v_mul_f32_e32 v34, v34, v72
	v_mul_f32_e32 v35, v35, v72
	v_mul_f32_e32 v32, v16, v32
	v_mul_f32_e32 v33, v17, v33
	v_mul_f32_e32 v34, v18, v34
	v_mul_f32_e32 v35, v19, v35
	v_cvt_pk_bf16_f32 v80, v32, v33
	v_cvt_pk_bf16_f32 v81, v34, v35
	global_store_dwordx2 v71, v[80:81], s[36:37] offset:1536
	s_add_u32 s36, s36, 0x400000
	s_addc_u32 s37, s37, 0
	global_load_dwordx4 v[20:23], v70, s[34:35]
	global_load_dwordx4 v[24:27], v70, s[34:35] offset:1024
	global_load_dwordx4 v[28:31], v70, s[34:35] offset:2048
	global_load_dwordx4 v[32:35], v70, s[34:35] offset:3072
	s_add_u32 s34, s34, 0x800000
	s_addc_u32 s35, s35, 0
	s_waitcnt vmcnt(12)
	v_mul_f32_e32 v72, v36, v36
	v_mul_f32_e32 v73, v37, v37
	v_fmac_f32_e32 v72, v38, v38
	v_fmac_f32_e32 v73, v39, v39
	v_fmac_f32_e32 v72, v40, v40
	v_fmac_f32_e32 v73, v41, v41
	v_fmac_f32_e32 v72, v42, v42
	v_fmac_f32_e32 v73, v43, v43
	v_fmac_f32_e32 v72, v44, v44
	v_fmac_f32_e32 v73, v45, v45
	v_fmac_f32_e32 v72, v46, v46
	v_fmac_f32_e32 v73, v47, v47
	v_fmac_f32_e32 v72, v48, v48
	v_fmac_f32_e32 v73, v49, v49
	v_fmac_f32_e32 v72, v50, v50
	v_fmac_f32_e32 v73, v51, v51
	v_add_f32_e32 v72, v72, v73
	s_nop 1
	v_add_f32_dpp v72, v72, v72 quad_perm:[1,0,3,2] row_mask:0xf bank_mask:0xf
	s_nop 1
	v_add_f32_dpp v72, v72, v72 quad_perm:[2,3,0,1] row_mask:0xf bank_mask:0xf
	s_nop 1
	v_add_f32_dpp v72, v72, v72 row_half_mirror row_mask:0xf bank_mask:0xf
	s_nop 1
	v_add_f32_dpp v72, v72, v72 row_mirror row_mask:0xf bank_mask:0xf
	s_nop 1
	v_add_f32_dpp v72, v72, v72 row_bcast:15 row_mask:0xa bank_mask:0xf
	s_nop 1
	v_add_f32_dpp v72, v72, v72 row_bcast:31 row_mask:0xc bank_mask:0xf
	s_nop 1
	v_readlane_b32 s3, v72, 63
	s_nop 1
	v_mov_b32_e32 v72, s3
	v_fmamk_f32 v72, v72, 0x3a800000, v172
	v_rsq_f32_e32 v72, v72
	s_nop 0
	v_mul_f32_e32 v36, v36, v72
	v_mul_f32_e32 v37, v37, v72
	v_mul_f32_e32 v38, v38, v72
	v_mul_f32_e32 v39, v39, v72
	v_mul_f32_e32 v36, v4, v36
	v_mul_f32_e32 v37, v5, v37
	v_mul_f32_e32 v38, v6, v38
	v_mul_f32_e32 v39, v7, v39
	v_cvt_pk_bf16_f32 v74, v36, v37
	v_cvt_pk_bf16_f32 v75, v38, v39
	global_store_dwordx2 v71, v[74:75], s[36:37]
	v_mul_f32_e32 v40, v40, v72
	v_mul_f32_e32 v41, v41, v72
	v_mul_f32_e32 v42, v42, v72
	v_mul_f32_e32 v43, v43, v72
	v_mul_f32_e32 v40, v8, v40
	v_mul_f32_e32 v41, v9, v41
	v_mul_f32_e32 v42, v10, v42
	v_mul_f32_e32 v43, v11, v43
	v_cvt_pk_bf16_f32 v76, v40, v41
	v_cvt_pk_bf16_f32 v77, v42, v43
	global_store_dwordx2 v71, v[76:77], s[36:37] offset:512
	v_mul_f32_e32 v44, v44, v72
	v_mul_f32_e32 v45, v45, v72
	v_mul_f32_e32 v46, v46, v72
	v_mul_f32_e32 v47, v47, v72
	v_mul_f32_e32 v44, v12, v44
	v_mul_f32_e32 v45, v13, v45
	v_mul_f32_e32 v46, v14, v46
	v_mul_f32_e32 v47, v15, v47
	v_cvt_pk_bf16_f32 v78, v44, v45
	v_cvt_pk_bf16_f32 v79, v46, v47
	global_store_dwordx2 v71, v[78:79], s[36:37] offset:1024
	v_mul_f32_e32 v48, v48, v72
	v_mul_f32_e32 v49, v49, v72
	v_mul_f32_e32 v50, v50, v72
	v_mul_f32_e32 v51, v51, v72
	v_mul_f32_e32 v48, v16, v48
	v_mul_f32_e32 v49, v17, v49
	v_mul_f32_e32 v50, v18, v50
	v_mul_f32_e32 v51, v19, v51
	v_cvt_pk_bf16_f32 v80, v48, v49
	v_cvt_pk_bf16_f32 v81, v50, v51
	global_store_dwordx2 v71, v[80:81], s[36:37] offset:1536
	s_add_u32 s36, s36, 0x400000
	s_addc_u32 s37, s37, 0
	global_load_dwordx4 v[36:39], v70, s[34:35]
	global_load_dwordx4 v[40:43], v70, s[34:35] offset:1024
	global_load_dwordx4 v[44:47], v70, s[34:35] offset:2048
	global_load_dwordx4 v[48:51], v70, s[34:35] offset:3072
	s_add_u32 s34, s34, 0x800000
	s_addc_u32 s35, s35, 0
	s_waitcnt vmcnt(16)
	v_mul_f32_e32 v72, v52, v52
	v_mul_f32_e32 v73, v53, v53
	v_fmac_f32_e32 v72, v54, v54
	v_fmac_f32_e32 v73, v55, v55
	v_fmac_f32_e32 v72, v56, v56
	v_fmac_f32_e32 v73, v57, v57
	v_fmac_f32_e32 v72, v58, v58
	v_fmac_f32_e32 v73, v59, v59
	v_fmac_f32_e32 v72, v60, v60
	v_fmac_f32_e32 v73, v61, v61
	v_fmac_f32_e32 v72, v62, v62
	v_fmac_f32_e32 v73, v63, v63
	v_fmac_f32_e32 v72, v64, v64
	v_fmac_f32_e32 v73, v65, v65
	v_fmac_f32_e32 v72, v66, v66
	v_fmac_f32_e32 v73, v67, v67
	v_add_f32_e32 v72, v72, v73
	s_nop 1
	v_add_f32_dpp v72, v72, v72 quad_perm:[1,0,3,2] row_mask:0xf bank_mask:0xf
	s_nop 1
	v_add_f32_dpp v72, v72, v72 quad_perm:[2,3,0,1] row_mask:0xf bank_mask:0xf
	s_nop 1
	v_add_f32_dpp v72, v72, v72 row_half_mirror row_mask:0xf bank_mask:0xf
	s_nop 1
	v_add_f32_dpp v72, v72, v72 row_mirror row_mask:0xf bank_mask:0xf
	s_nop 1
	v_add_f32_dpp v72, v72, v72 row_bcast:15 row_mask:0xa bank_mask:0xf
	s_nop 1
	v_add_f32_dpp v72, v72, v72 row_bcast:31 row_mask:0xc bank_mask:0xf
	s_nop 1
	v_readlane_b32 s3, v72, 63
	s_nop 1
	v_mov_b32_e32 v72, s3
	v_fmamk_f32 v72, v72, 0x3a800000, v172
	v_rsq_f32_e32 v72, v72
	s_nop 0
	v_mul_f32_e32 v52, v52, v72
	v_mul_f32_e32 v53, v53, v72
	v_mul_f32_e32 v54, v54, v72
	v_mul_f32_e32 v55, v55, v72
	v_mul_f32_e32 v52, v4, v52
	v_mul_f32_e32 v53, v5, v53
	v_mul_f32_e32 v54, v6, v54
	v_mul_f32_e32 v55, v7, v55
	v_cvt_pk_bf16_f32 v74, v52, v53
	v_cvt_pk_bf16_f32 v75, v54, v55
	global_store_dwordx2 v71, v[74:75], s[36:37]
	v_mul_f32_e32 v56, v56, v72
	v_mul_f32_e32 v57, v57, v72
	v_mul_f32_e32 v58, v58, v72
	v_mul_f32_e32 v59, v59, v72
	v_mul_f32_e32 v56, v8, v56
	v_mul_f32_e32 v57, v9, v57
	v_mul_f32_e32 v58, v10, v58
	v_mul_f32_e32 v59, v11, v59
	v_cvt_pk_bf16_f32 v76, v56, v57
	v_cvt_pk_bf16_f32 v77, v58, v59
	global_store_dwordx2 v71, v[76:77], s[36:37] offset:512
	v_mul_f32_e32 v60, v60, v72
	v_mul_f32_e32 v61, v61, v72
	v_mul_f32_e32 v62, v62, v72
	v_mul_f32_e32 v63, v63, v72
	v_mul_f32_e32 v60, v12, v60
	v_mul_f32_e32 v61, v13, v61
	v_mul_f32_e32 v62, v14, v62
	v_mul_f32_e32 v63, v15, v63
	v_cvt_pk_bf16_f32 v78, v60, v61
	v_cvt_pk_bf16_f32 v79, v62, v63
	global_store_dwordx2 v71, v[78:79], s[36:37] offset:1024
	v_mul_f32_e32 v64, v64, v72
	v_mul_f32_e32 v65, v65, v72
	v_mul_f32_e32 v66, v66, v72
	v_mul_f32_e32 v67, v67, v72
	v_mul_f32_e32 v64, v16, v64
	v_mul_f32_e32 v65, v17, v65
	v_mul_f32_e32 v66, v18, v66
	v_mul_f32_e32 v67, v19, v67
	v_cvt_pk_bf16_f32 v80, v64, v65
	v_cvt_pk_bf16_f32 v81, v66, v67
	global_store_dwordx2 v71, v[80:81], s[36:37] offset:1536
	s_add_u32 s36, s36, 0x400000
	s_addc_u32 s37, s37, 0
	global_load_dwordx4 v[52:55], v70, s[34:35]
	global_load_dwordx4 v[56:59], v70, s[34:35] offset:1024
	global_load_dwordx4 v[60:63], v70, s[34:35] offset:2048
	global_load_dwordx4 v[64:67], v70, s[34:35] offset:3072
	s_add_u32 s34, s34, 0x800000
	s_addc_u32 s35, s35, 0
	s_waitcnt vmcnt(16)
	v_mul_f32_e32 v72, v20, v20
	v_mul_f32_e32 v73, v21, v21
	v_fmac_f32_e32 v72, v22, v22
	v_fmac_f32_e32 v73, v23, v23
	v_fmac_f32_e32 v72, v24, v24
	v_fmac_f32_e32 v73, v25, v25
	v_fmac_f32_e32 v72, v26, v26
	v_fmac_f32_e32 v73, v27, v27
	v_fmac_f32_e32 v72, v28, v28
	v_fmac_f32_e32 v73, v29, v29
	v_fmac_f32_e32 v72, v30, v30
	v_fmac_f32_e32 v73, v31, v31
	v_fmac_f32_e32 v72, v32, v32
	v_fmac_f32_e32 v73, v33, v33
	v_fmac_f32_e32 v72, v34, v34
	v_fmac_f32_e32 v73, v35, v35
	v_add_f32_e32 v72, v72, v73
	s_nop 1
	v_add_f32_dpp v72, v72, v72 quad_perm:[1,0,3,2] row_mask:0xf bank_mask:0xf
	s_nop 1
	v_add_f32_dpp v72, v72, v72 quad_perm:[2,3,0,1] row_mask:0xf bank_mask:0xf
	s_nop 1
	v_add_f32_dpp v72, v72, v72 row_half_mirror row_mask:0xf bank_mask:0xf
	s_nop 1
	v_add_f32_dpp v72, v72, v72 row_mirror row_mask:0xf bank_mask:0xf
	s_nop 1
	v_add_f32_dpp v72, v72, v72 row_bcast:15 row_mask:0xa bank_mask:0xf
	s_nop 1
	v_add_f32_dpp v72, v72, v72 row_bcast:31 row_mask:0xc bank_mask:0xf
	s_nop 1
	v_readlane_b32 s3, v72, 63
	s_nop 1
	v_mov_b32_e32 v72, s3
	v_fmamk_f32 v72, v72, 0x3a800000, v172
	v_rsq_f32_e32 v72, v72
	s_nop 0
	v_mul_f32_e32 v20, v20, v72
	v_mul_f32_e32 v21, v21, v72
	v_mul_f32_e32 v22, v22, v72
	v_mul_f32_e32 v23, v23, v72
	v_mul_f32_e32 v20, v4, v20
	v_mul_f32_e32 v21, v5, v21
	v_mul_f32_e32 v22, v6, v22
	v_mul_f32_e32 v23, v7, v23
	v_cvt_pk_bf16_f32 v74, v20, v21
	v_cvt_pk_bf16_f32 v75, v22, v23
	global_store_dwordx2 v71, v[74:75], s[36:37]
	v_mul_f32_e32 v24, v24, v72
	v_mul_f32_e32 v25, v25, v72
	v_mul_f32_e32 v26, v26, v72
	v_mul_f32_e32 v27, v27, v72
	v_mul_f32_e32 v24, v8, v24
	v_mul_f32_e32 v25, v9, v25
	v_mul_f32_e32 v26, v10, v26
	v_mul_f32_e32 v27, v11, v27
	v_cvt_pk_bf16_f32 v76, v24, v25
	v_cvt_pk_bf16_f32 v77, v26, v27
	global_store_dwordx2 v71, v[76:77], s[36:37] offset:512
	v_mul_f32_e32 v28, v28, v72
	v_mul_f32_e32 v29, v29, v72
	v_mul_f32_e32 v30, v30, v72
	v_mul_f32_e32 v31, v31, v72
	v_mul_f32_e32 v28, v12, v28
	v_mul_f32_e32 v29, v13, v29
	v_mul_f32_e32 v30, v14, v30
	v_mul_f32_e32 v31, v15, v31
	v_cvt_pk_bf16_f32 v78, v28, v29
	v_cvt_pk_bf16_f32 v79, v30, v31
	global_store_dwordx2 v71, v[78:79], s[36:37] offset:1024
	v_mul_f32_e32 v32, v32, v72
	v_mul_f32_e32 v33, v33, v72
	v_mul_f32_e32 v34, v34, v72
	v_mul_f32_e32 v35, v35, v72
	v_mul_f32_e32 v32, v16, v32
	v_mul_f32_e32 v33, v17, v33
	v_mul_f32_e32 v34, v18, v34
	v_mul_f32_e32 v35, v19, v35
	v_cvt_pk_bf16_f32 v80, v32, v33
	v_cvt_pk_bf16_f32 v81, v34, v35
	global_store_dwordx2 v71, v[80:81], s[36:37] offset:1536
	s_add_u32 s36, s36, 0x400000
	s_addc_u32 s37, s37, 0
	global_load_dwordx4 v[20:23], v70, s[34:35]
	global_load_dwordx4 v[24:27], v70, s[34:35] offset:1024
	global_load_dwordx4 v[28:31], v70, s[34:35] offset:2048
	global_load_dwordx4 v[32:35], v70, s[34:35] offset:3072
	s_add_u32 s34, s34, 0x800000
	s_addc_u32 s35, s35, 0
	s_waitcnt vmcnt(16)
	v_mul_f32_e32 v72, v36, v36
	v_mul_f32_e32 v73, v37, v37
	v_fmac_f32_e32 v72, v38, v38
	v_fmac_f32_e32 v73, v39, v39
	v_fmac_f32_e32 v72, v40, v40
	v_fmac_f32_e32 v73, v41, v41
	v_fmac_f32_e32 v72, v42, v42
	v_fmac_f32_e32 v73, v43, v43
	v_fmac_f32_e32 v72, v44, v44
	v_fmac_f32_e32 v73, v45, v45
	v_fmac_f32_e32 v72, v46, v46
	v_fmac_f32_e32 v73, v47, v47
	v_fmac_f32_e32 v72, v48, v48
	v_fmac_f32_e32 v73, v49, v49
	v_fmac_f32_e32 v72, v50, v50
	v_fmac_f32_e32 v73, v51, v51
	v_add_f32_e32 v72, v72, v73
	s_nop 1
	v_add_f32_dpp v72, v72, v72 quad_perm:[1,0,3,2] row_mask:0xf bank_mask:0xf
	s_nop 1
	v_add_f32_dpp v72, v72, v72 quad_perm:[2,3,0,1] row_mask:0xf bank_mask:0xf
	s_nop 1
	v_add_f32_dpp v72, v72, v72 row_half_mirror row_mask:0xf bank_mask:0xf
	s_nop 1
	v_add_f32_dpp v72, v72, v72 row_mirror row_mask:0xf bank_mask:0xf
	s_nop 1
	v_add_f32_dpp v72, v72, v72 row_bcast:15 row_mask:0xa bank_mask:0xf
	s_nop 1
	v_add_f32_dpp v72, v72, v72 row_bcast:31 row_mask:0xc bank_mask:0xf
	s_nop 1
	v_readlane_b32 s3, v72, 63
	s_nop 1
	v_mov_b32_e32 v72, s3
	v_fmamk_f32 v72, v72, 0x3a800000, v172
	v_rsq_f32_e32 v72, v72
	s_nop 0
	v_mul_f32_e32 v36, v36, v72
	v_mul_f32_e32 v37, v37, v72
	v_mul_f32_e32 v38, v38, v72
	v_mul_f32_e32 v39, v39, v72
	v_mul_f32_e32 v36, v4, v36
	v_mul_f32_e32 v37, v5, v37
	v_mul_f32_e32 v38, v6, v38
	v_mul_f32_e32 v39, v7, v39
	v_cvt_pk_bf16_f32 v74, v36, v37
	v_cvt_pk_bf16_f32 v75, v38, v39
	global_store_dwordx2 v71, v[74:75], s[36:37]
	v_mul_f32_e32 v40, v40, v72
	v_mul_f32_e32 v41, v41, v72
	v_mul_f32_e32 v42, v42, v72
	v_mul_f32_e32 v43, v43, v72
	v_mul_f32_e32 v40, v8, v40
	v_mul_f32_e32 v41, v9, v41
	v_mul_f32_e32 v42, v10, v42
	v_mul_f32_e32 v43, v11, v43
	v_cvt_pk_bf16_f32 v76, v40, v41
	v_cvt_pk_bf16_f32 v77, v42, v43
	global_store_dwordx2 v71, v[76:77], s[36:37] offset:512
	v_mul_f32_e32 v44, v44, v72
	v_mul_f32_e32 v45, v45, v72
	v_mul_f32_e32 v46, v46, v72
	v_mul_f32_e32 v47, v47, v72
	v_mul_f32_e32 v44, v12, v44
	v_mul_f32_e32 v45, v13, v45
	v_mul_f32_e32 v46, v14, v46
	v_mul_f32_e32 v47, v15, v47
	v_cvt_pk_bf16_f32 v78, v44, v45
	v_cvt_pk_bf16_f32 v79, v46, v47
	global_store_dwordx2 v71, v[78:79], s[36:37] offset:1024
	v_mul_f32_e32 v48, v48, v72
	v_mul_f32_e32 v49, v49, v72
	v_mul_f32_e32 v50, v50, v72
	v_mul_f32_e32 v51, v51, v72
	v_mul_f32_e32 v48, v16, v48
	v_mul_f32_e32 v49, v17, v49
	v_mul_f32_e32 v50, v18, v50
	v_mul_f32_e32 v51, v19, v51
	v_cvt_pk_bf16_f32 v80, v48, v49
	v_cvt_pk_bf16_f32 v81, v50, v51
	global_store_dwordx2 v71, v[80:81], s[36:37] offset:1536
	s_add_u32 s36, s36, 0x400000
	s_addc_u32 s37, s37, 0
	global_load_dwordx4 v[36:39], v70, s[34:35]
	global_load_dwordx4 v[40:43], v70, s[34:35] offset:1024
	global_load_dwordx4 v[44:47], v70, s[34:35] offset:2048
	global_load_dwordx4 v[48:51], v70, s[34:35] offset:3072
	s_add_u32 s34, s34, 0x800000
	s_addc_u32 s35, s35, 0
	s_waitcnt vmcnt(16)
	v_mul_f32_e32 v72, v52, v52
	v_mul_f32_e32 v73, v53, v53
	v_fmac_f32_e32 v72, v54, v54
	v_fmac_f32_e32 v73, v55, v55
	v_fmac_f32_e32 v72, v56, v56
	v_fmac_f32_e32 v73, v57, v57
	v_fmac_f32_e32 v72, v58, v58
	v_fmac_f32_e32 v73, v59, v59
	v_fmac_f32_e32 v72, v60, v60
	v_fmac_f32_e32 v73, v61, v61
	v_fmac_f32_e32 v72, v62, v62
	v_fmac_f32_e32 v73, v63, v63
	v_fmac_f32_e32 v72, v64, v64
	v_fmac_f32_e32 v73, v65, v65
	v_fmac_f32_e32 v72, v66, v66
	v_fmac_f32_e32 v73, v67, v67
	v_add_f32_e32 v72, v72, v73
	s_nop 1
	v_add_f32_dpp v72, v72, v72 quad_perm:[1,0,3,2] row_mask:0xf bank_mask:0xf
	s_nop 1
	v_add_f32_dpp v72, v72, v72 quad_perm:[2,3,0,1] row_mask:0xf bank_mask:0xf
	s_nop 1
	v_add_f32_dpp v72, v72, v72 row_half_mirror row_mask:0xf bank_mask:0xf
	s_nop 1
	v_add_f32_dpp v72, v72, v72 row_mirror row_mask:0xf bank_mask:0xf
	s_nop 1
	v_add_f32_dpp v72, v72, v72 row_bcast:15 row_mask:0xa bank_mask:0xf
	s_nop 1
	v_add_f32_dpp v72, v72, v72 row_bcast:31 row_mask:0xc bank_mask:0xf
	s_nop 1
	v_readlane_b32 s3, v72, 63
	s_nop 1
	v_mov_b32_e32 v72, s3
	v_fmamk_f32 v72, v72, 0x3a800000, v172
	v_rsq_f32_e32 v72, v72
	s_nop 0
	v_mul_f32_e32 v52, v52, v72
	v_mul_f32_e32 v53, v53, v72
	v_mul_f32_e32 v54, v54, v72
	v_mul_f32_e32 v55, v55, v72
	v_mul_f32_e32 v52, v4, v52
	v_mul_f32_e32 v53, v5, v53
	v_mul_f32_e32 v54, v6, v54
	v_mul_f32_e32 v55, v7, v55
	v_cvt_pk_bf16_f32 v74, v52, v53
	v_cvt_pk_bf16_f32 v75, v54, v55
	global_store_dwordx2 v71, v[74:75], s[36:37]
	v_mul_f32_e32 v56, v56, v72
	v_mul_f32_e32 v57, v57, v72
	v_mul_f32_e32 v58, v58, v72
	v_mul_f32_e32 v59, v59, v72
	v_mul_f32_e32 v56, v8, v56
	v_mul_f32_e32 v57, v9, v57
	v_mul_f32_e32 v58, v10, v58
	v_mul_f32_e32 v59, v11, v59
	v_cvt_pk_bf16_f32 v76, v56, v57
	v_cvt_pk_bf16_f32 v77, v58, v59
	global_store_dwordx2 v71, v[76:77], s[36:37] offset:512
	v_mul_f32_e32 v60, v60, v72
	v_mul_f32_e32 v61, v61, v72
	v_mul_f32_e32 v62, v62, v72
	v_mul_f32_e32 v63, v63, v72
	v_mul_f32_e32 v60, v12, v60
	v_mul_f32_e32 v61, v13, v61
	v_mul_f32_e32 v62, v14, v62
	v_mul_f32_e32 v63, v15, v63
	v_cvt_pk_bf16_f32 v78, v60, v61
	v_cvt_pk_bf16_f32 v79, v62, v63
	global_store_dwordx2 v71, v[78:79], s[36:37] offset:1024
	v_mul_f32_e32 v64, v64, v72
	v_mul_f32_e32 v65, v65, v72
	v_mul_f32_e32 v66, v66, v72
	v_mul_f32_e32 v67, v67, v72
	v_mul_f32_e32 v64, v16, v64
	v_mul_f32_e32 v65, v17, v65
	v_mul_f32_e32 v66, v18, v66
	v_mul_f32_e32 v67, v19, v67
	v_cvt_pk_bf16_f32 v80, v64, v65
	v_cvt_pk_bf16_f32 v81, v66, v67
	global_store_dwordx2 v71, v[80:81], s[36:37] offset:1536
	s_add_u32 s36, s36, 0x400000
	s_addc_u32 s37, s37, 0
	s_cmpk_lt_u32 s0, 0x100
	s_cbranch_scc0 .Lnrm_mix_nol8
	global_load_dwordx4 v[52:55], v70, s[34:35]
	global_load_dwordx4 v[56:59], v70, s[34:35] offset:1024
	global_load_dwordx4 v[60:63], v70, s[34:35] offset:2048
	global_load_dwordx4 v[64:67], v70, s[34:35] offset:3072
	s_add_u32 s34, s34, 0x800000
	s_addc_u32 s35, s35, 0

.LBB0_2296:
	s_or_b64 exec, exec, s[0:1]
	s_mov_b64 s[6:7], s[84:85]
	v_mov_b32_e32 v0, v196
	s_waitcnt lgkmcnt(0)
	v_mov_b32_e32 v2, v196
	s_barrier
	v_readlane_b32 s0, v249, 1
	s_nop 0
	s_cmpk_lg_u32 s0, 0x200
	s_cbranch_scc1 .Lnrm_ffn_orig
	v_readlane_b32 s0, v249, 5
	v_lshrrev_b32_e32 v68, 6, v196
	s_load_dwordx4 s[28:31], s[84:85], 0x130
	s_load_dwordx2 s[32:33], s[84:85], 0xa8
	v_and_b32_e32 v69, 63, v196
	v_readfirstlane_b32 s1, v68
	v_lshlrev_b32_e32 v70, 4, v69
	v_lshlrev_b32_e32 v71, 3, v69
	s_add_i32 s0, s0, s1
	s_lshr_b32 s2, s0, 2
	s_and_b32 s3, s2, 7
	s_lshr_b32 s2, s2, 3
	s_lshl_b32 s2, s2, 2
	s_add_i32 s2, s2, s1
	s_lshl_b32 s0, s3, 7
	s_and_b32 s3, s2, 0x7f
	s_add_i32 s0, s0, s3
	s_lshr_b32 s2, s2, 7
	s_lshl_b32 s2, s2, 10
	s_add_i32 s0, s0, s2
	s_waitcnt lgkmcnt(0)
	s_lshl_b32 s2, s72, 2
	s_add_u32 s32, s32, s2
	s_addc_u32 s33, s33, 0
	global_load_dwordx4 v[4:7], v70, s[32:33]
	global_load_dwordx4 v[8:11], v70, s[32:33] offset:1024
	global_load_dwordx4 v[12:15], v70, s[32:33] offset:2048
	global_load_dwordx4 v[16:19], v70, s[32:33] offset:3072
	s_lshl_b32 s2, s0, 12
	s_add_u32 s34, s28, s2
	s_addc_u32 s35, s29, 0
	s_lshl_b32 s2, s0, 11
	s_add_u32 s36, s30, s2
	s_addc_u32 s37, s31, 0
	global_load_dwordx4 v[20:23], v70, s[34:35]
	global_load_dwordx4 v[24:27], v70, s[34:35] offset:1024
	global_load_dwordx4 v[28:31], v70, s[34:35] offset:2048
	global_load_dwordx4 v[32:35], v70, s[34:35] offset:3072
	s_add_u32 s34, s34, 0x800000
	s_addc_u32 s35, s35, 0
	global_load_dwordx4 v[36:39], v70, s[34:35]
	global_load_dwordx4 v[40:43], v70, s[34:35] offset:1024
	global_load_dwordx4 v[44:47], v70, s[34:35] offset:2048
	global_load_dwordx4 v[48:51], v70, s[34:35] offset:3072
	s_add_u32 s34, s34, 0x800000
	s_addc_u32 s35, s35, 0
	global_load_dwordx4 v[52:55], v70, s[34:35]
	global_load_dwordx4 v[56:59], v70, s[34:35] offset:1024
	global_load_dwordx4 v[60:63], v70, s[34:35] offset:2048
	global_load_dwordx4 v[64:67], v70, s[34:35] offset:3072
	s_add_u32 s34, s34, 0x800000
	s_addc_u32 s35, s35, 0
	s_waitcnt vmcnt(8)
	v_mul_f32_e32 v72, v20, v20
	v_mul_f32_e32 v73, v21, v21
	v_fmac_f32_e32 v72, v22, v22
	v_fmac_f32_e32 v73, v23, v23
	v_fmac_f32_e32 v72, v24, v24
	v_fmac_f32_e32 v73, v25, v25
	v_fmac_f32_e32 v72, v26, v26
	v_fmac_f32_e32 v73, v27, v27
	v_fmac_f32_e32 v72, v28, v28
	v_fmac_f32_e32 v73, v29, v29
	v_fmac_f32_e32 v72, v30, v30
	v_fmac_f32_e32 v73, v31, v31
	v_fmac_f32_e32 v72, v32, v32
	v_fmac_f32_e32 v73, v33, v33
	v_fmac_f32_e32 v72, v34, v34
	v_fmac_f32_e32 v73, v35, v35
	v_add_f32_e32 v72, v72, v73
	s_nop 1
	v_add_f32_dpp v72, v72, v72 quad_perm:[1,0,3,2] row_mask:0xf bank_mask:0xf
	s_nop 1
	v_add_f32_dpp v72, v72, v72 quad_perm:[2,3,0,1] row_mask:0xf bank_mask:0xf
	s_nop 1
	v_add_f32_dpp v72, v72, v72 row_half_mirror row_mask:0xf bank_mask:0xf
	s_nop 1
	v_add_f32_dpp v72, v72, v72 row_mirror row_mask:0xf bank_mask:0xf
	s_nop 1
	v_add_f32_dpp v72, v72, v72 row_bcast:15 row_mask:0xa bank_mask:0xf
	s_nop 1
	v_add_f32_dpp v72, v72, v72 row_bcast:31 row_mask:0xc bank_mask:0xf
	s_nop 1
	v_readlane_b32 s3, v72, 63
	s_nop 1
	v_mov_b32_e32 v72, s3
	v_fmamk_f32 v72, v72, 0x3a800000, v172
	v_rsq_f32_e32 v72, v72
	s_nop 0
	v_mul_f32_e32 v20, v20, v72
	v_mul_f32_e32 v21, v21, v72
	v_mul_f32_e32 v22, v22, v72
	v_mul_f32_e32 v23, v23, v72
	v_mul_f32_e32 v20, v4, v20
	v_mul_f32_e32 v21, v5, v21
	v_mul_f32_e32 v22, v6, v22
	v_mul_f32_e32 v23, v7, v23
	v_cvt_pk_bf16_f32 v74, v20, v21
	v_cvt_pk_bf16_f32 v75, v22, v23
	global_store_dwordx2 v71, v[74:75], s[36:37]
	v_mul_f32_e32 v24, v24, v72
	v_mul_f32_e32 v25, v25, v72
	v_mul_f32_e32 v26, v26, v72
	v_mul_f32_e32 v27, v27, v72
	v_mul_f32_e32 v24, v8, v24
	v_mul_f32_e32 v25, v9, v25
	v_mul_f32_e32 v26, v10, v26
	v_mul_f32_e32 v27, v11, v27
	v_cvt_pk_bf16_f32 v76, v24, v25
	v_cvt_pk_bf16_f32 v77, v26, v27
	global_store_dwordx2 v71, v[76:77], s[36:37] offset:512
	v_mul_f32_e32 v28, v28, v72
	v_mul_f32_e32 v29, v29, v72
	v_mul_f32_e32 v30, v30, v72
	v_mul_f32_e32 v31, v31, v72
	v_mul_f32_e32 v28, v12, v28
	v_mul_f32_e32 v29, v13, v29
	v_mul_f32_e32 v30, v14, v30
	v_mul_f32_e32 v31, v15, v31
	v_cvt_pk_bf16_f32 v78, v28, v29
	v_cvt_pk_bf16_f32 v79, v30, v31
	global_store_dwordx2 v71, v[78:79], s[36:37] offset:1024
	v_mul_f32_e32 v32, v32, v72
	v_mul_f32_e32 v33, v33, v72
	v_mul_f32_e32 v34, v34, v72
	v_mul_f32_e32 v35, v35, v72
	v_mul_f32_e32 v32, v16, v32
	v_mul_f32_e32 v33, v17, v33
	v_mul_f32_e32 v34, v18, v34
	v_mul_f32_e32 v35, v19, v35
	v_cvt_pk_bf16_f32 v80, v32, v33
	v_cvt_pk_bf16_f32 v81, v34, v35
	global_store_dwordx2 v71, v[80:81], s[36:37] offset:1536
	s_add_u32 s36, s36, 0x400000
	s_addc_u32 s37, s37, 0
	global_load_dwordx4 v[20:23], v70, s[34:35]
	global_load_dwordx4 v[24:27], v70, s[34:35] offset:1024
	global_load_dwordx4 v[28:31], v70, s[34:35] offset:2048
	global_load_dwordx4 v[32:35], v70, s[34:35] offset:3072
	s_add_u32 s34, s34, 0x800000
	s_addc_u32 s35, s35, 0
	s_waitcnt vmcnt(12)
	v_mul_f32_e32 v72, v36, v36
	v_mul_f32_e32 v73, v37, v37
	v_fmac_f32_e32 v72, v38, v38
	v_fmac_f32_e32 v73, v39, v39
	v_fmac_f32_e32 v72, v40, v40
	v_fmac_f32_e32 v73, v41, v41
	v_fmac_f32_e32 v72, v42, v42
	v_fmac_f32_e32 v73, v43, v43
	v_fmac_f32_e32 v72, v44, v44
	v_fmac_f32_e32 v73, v45, v45
	v_fmac_f32_e32 v72, v46, v46
	v_fmac_f32_e32 v73, v47, v47
	v_fmac_f32_e32 v72, v48, v48
	v_fmac_f32_e32 v73, v49, v49
	v_fmac_f32_e32 v72, v50, v50
	v_fmac_f32_e32 v73, v51, v51
	v_add_f32_e32 v72, v72, v73
	s_nop 1
	v_add_f32_dpp v72, v72, v72 quad_perm:[1,0,3,2] row_mask:0xf bank_mask:0xf
	s_nop 1
	v_add_f32_dpp v72, v72, v72 quad_perm:[2,3,0,1] row_mask:0xf bank_mask:0xf
	s_nop 1
	v_add_f32_dpp v72, v72, v72 row_half_mirror row_mask:0xf bank_mask:0xf
	s_nop 1
	v_add_f32_dpp v72, v72, v72 row_mirror row_mask:0xf bank_mask:0xf
	s_nop 1
	v_add_f32_dpp v72, v72, v72 row_bcast:15 row_mask:0xa bank_mask:0xf
	s_nop 1
	v_add_f32_dpp v72, v72, v72 row_bcast:31 row_mask:0xc bank_mask:0xf
	s_nop 1
	v_readlane_b32 s3, v72, 63
	s_nop 1
	v_mov_b32_e32 v72, s3
	v_fmamk_f32 v72, v72, 0x3a800000, v172
	v_rsq_f32_e32 v72, v72
	s_nop 0
	v_mul_f32_e32 v36, v36, v72
	v_mul_f32_e32 v37, v37, v72
	v_mul_f32_e32 v38, v38, v72
	v_mul_f32_e32 v39, v39, v72
	v_mul_f32_e32 v36, v4, v36
	v_mul_f32_e32 v37, v5, v37
	v_mul_f32_e32 v38, v6, v38
	v_mul_f32_e32 v39, v7, v39
	v_cvt_pk_bf16_f32 v74, v36, v37
	v_cvt_pk_bf16_f32 v75, v38, v39
	global_store_dwordx2 v71, v[74:75], s[36:37]
	v_mul_f32_e32 v40, v40, v72
	v_mul_f32_e32 v41, v41, v72
	v_mul_f32_e32 v42, v42, v72
	v_mul_f32_e32 v43, v43, v72
	v_mul_f32_e32 v40, v8, v40
	v_mul_f32_e32 v41, v9, v41
	v_mul_f32_e32 v42, v10, v42
	v_mul_f32_e32 v43, v11, v43
	v_cvt_pk_bf16_f32 v76, v40, v41
	v_cvt_pk_bf16_f32 v77, v42, v43
	global_store_dwordx2 v71, v[76:77], s[36:37] offset:512
	v_mul_f32_e32 v44, v44, v72
	v_mul_f32_e32 v45, v45, v72
	v_mul_f32_e32 v46, v46, v72
	v_mul_f32_e32 v47, v47, v72
	v_mul_f32_e32 v44, v12, v44
	v_mul_f32_e32 v45, v13, v45
	v_mul_f32_e32 v46, v14, v46
	v_mul_f32_e32 v47, v15, v47
	v_cvt_pk_bf16_f32 v78, v44, v45
	v_cvt_pk_bf16_f32 v79, v46, v47
	global_store_dwordx2 v71, v[78:79], s[36:37] offset:1024
	v_mul_f32_e32 v48, v48, v72
	v_mul_f32_e32 v49, v49, v72
	v_mul_f32_e32 v50, v50, v72
	v_mul_f32_e32 v51, v51, v72
	v_mul_f32_e32 v48, v16, v48
	v_mul_f32_e32 v49, v17, v49
	v_mul_f32_e32 v50, v18, v50
	v_mul_f32_e32 v51, v19, v51
	v_cvt_pk_bf16_f32 v80, v48, v49
	v_cvt_pk_bf16_f32 v81, v50, v51
	global_store_dwordx2 v71, v[80:81], s[36:37] offset:1536
	s_add_u32 s36, s36, 0x400000
	s_addc_u32 s37, s37, 0
	global_load_dwordx4 v[36:39], v70, s[34:35]
	global_load_dwordx4 v[40:43], v70, s[34:35] offset:1024
	global_load_dwordx4 v[44:47], v70, s[34:35] offset:2048
	global_load_dwordx4 v[48:51], v70, s[34:35] offset:3072
	s_add_u32 s34, s34, 0x800000
	s_addc_u32 s35, s35, 0
	s_waitcnt vmcnt(16)
	v_mul_f32_e32 v72, v52, v52
	v_mul_f32_e32 v73, v53, v53
	v_fmac_f32_e32 v72, v54, v54
	v_fmac_f32_e32 v73, v55, v55
	v_fmac_f32_e32 v72, v56, v56
	v_fmac_f32_e32 v73, v57, v57
	v_fmac_f32_e32 v72, v58, v58
	v_fmac_f32_e32 v73, v59, v59
	v_fmac_f32_e32 v72, v60, v60
	v_fmac_f32_e32 v73, v61, v61
	v_fmac_f32_e32 v72, v62, v62
	v_fmac_f32_e32 v73, v63, v63
	v_fmac_f32_e32 v72, v64, v64
	v_fmac_f32_e32 v73, v65, v65
	v_fmac_f32_e32 v72, v66, v66
	v_fmac_f32_e32 v73, v67, v67
	v_add_f32_e32 v72, v72, v73
	s_nop 1
	v_add_f32_dpp v72, v72, v72 quad_perm:[1,0,3,2] row_mask:0xf bank_mask:0xf
	s_nop 1
	v_add_f32_dpp v72, v72, v72 quad_perm:[2,3,0,1] row_mask:0xf bank_mask:0xf
	s_nop 1
	v_add_f32_dpp v72, v72, v72 row_half_mirror row_mask:0xf bank_mask:0xf
	s_nop 1
	v_add_f32_dpp v72, v72, v72 row_mirror row_mask:0xf bank_mask:0xf
	s_nop 1
	v_add_f32_dpp v72, v72, v72 row_bcast:15 row_mask:0xa bank_mask:0xf
	s_nop 1
	v_add_f32_dpp v72, v72, v72 row_bcast:31 row_mask:0xc bank_mask:0xf
	s_nop 1
	v_readlane_b32 s3, v72, 63
	s_nop 1
	v_mov_b32_e32 v72, s3
	v_fmamk_f32 v72, v72, 0x3a800000, v172
	v_rsq_f32_e32 v72, v72
	s_nop 0
	v_mul_f32_e32 v52, v52, v72
	v_mul_f32_e32 v53, v53, v72
	v_mul_f32_e32 v54, v54, v72
	v_mul_f32_e32 v55, v55, v72
	v_mul_f32_e32 v52, v4, v52
	v_mul_f32_e32 v53, v5, v53
	v_mul_f32_e32 v54, v6, v54
	v_mul_f32_e32 v55, v7, v55
	v_cvt_pk_bf16_f32 v74, v52, v53
	v_cvt_pk_bf16_f32 v75, v54, v55
	global_store_dwordx2 v71, v[74:75], s[36:37]
	v_mul_f32_e32 v56, v56, v72
	v_mul_f32_e32 v57, v57, v72
	v_mul_f32_e32 v58, v58, v72
	v_mul_f32_e32 v59, v59, v72
	v_mul_f32_e32 v56, v8, v56
	v_mul_f32_e32 v57, v9, v57
	v_mul_f32_e32 v58, v10, v58
	v_mul_f32_e32 v59, v11, v59
	v_cvt_pk_bf16_f32 v76, v56, v57
	v_cvt_pk_bf16_f32 v77, v58, v59
	global_store_dwordx2 v71, v[76:77], s[36:37] offset:512
	v_mul_f32_e32 v60, v60, v72
	v_mul_f32_e32 v61, v61, v72
	v_mul_f32_e32 v62, v62, v72
	v_mul_f32_e32 v63, v63, v72
	v_mul_f32_e32 v60, v12, v60
	v_mul_f32_e32 v61, v13, v61
	v_mul_f32_e32 v62, v14, v62
	v_mul_f32_e32 v63, v15, v63
	v_cvt_pk_bf16_f32 v78, v60, v61
	v_cvt_pk_bf16_f32 v79, v62, v63
	global_store_dwordx2 v71, v[78:79], s[36:37] offset:1024
	v_mul_f32_e32 v64, v64, v72
	v_mul_f32_e32 v65, v65, v72
	v_mul_f32_e32 v66, v66, v72
	v_mul_f32_e32 v67, v67, v72
	v_mul_f32_e32 v64, v16, v64
	v_mul_f32_e32 v65, v17, v65
	v_mul_f32_e32 v66, v18, v66
	v_mul_f32_e32 v67, v19, v67
	v_cvt_pk_bf16_f32 v80, v64, v65
	v_cvt_pk_bf16_f32 v81, v66, v67
	global_store_dwordx2 v71, v[80:81], s[36:37] offset:1536
	s_add_u32 s36, s36, 0x400000
	s_addc_u32 s37, s37, 0
	global_load_dwordx4 v[52:55], v70, s[34:35]
	global_load_dwordx4 v[56:59], v70, s[34:35] offset:1024
	global_load_dwordx4 v[60:63], v70, s[34:35] offset:2048
	global_load_dwordx4 v[64:67], v70, s[34:35] offset:3072
	s_add_u32 s34, s34, 0x800000
	s_addc_u32 s35, s35, 0
	s_waitcnt vmcnt(16)
	v_mul_f32_e32 v72, v20, v20
	v_mul_f32_e32 v73, v21, v21
	v_fmac_f32_e32 v72, v22, v22
	v_fmac_f32_e32 v73, v23, v23
	v_fmac_f32_e32 v72, v24, v24
	v_fmac_f32_e32 v73, v25, v25
	v_fmac_f32_e32 v72, v26, v26
	v_fmac_f32_e32 v73, v27, v27
	v_fmac_f32_e32 v72, v28, v28
	v_fmac_f32_e32 v73, v29, v29
	v_fmac_f32_e32 v72, v30, v30
	v_fmac_f32_e32 v73, v31, v31
	v_fmac_f32_e32 v72, v32, v32
	v_fmac_f32_e32 v73, v33, v33
	v_fmac_f32_e32 v72, v34, v34
	v_fmac_f32_e32 v73, v35, v35
	v_add_f32_e32 v72, v72, v73
	s_nop 1
	v_add_f32_dpp v72, v72, v72 quad_perm:[1,0,3,2] row_mask:0xf bank_mask:0xf
	s_nop 1
	v_add_f32_dpp v72, v72, v72 quad_perm:[2,3,0,1] row_mask:0xf bank_mask:0xf
	s_nop 1
	v_add_f32_dpp v72, v72, v72 row_half_mirror row_mask:0xf bank_mask:0xf
	s_nop 1
	v_add_f32_dpp v72, v72, v72 row_mirror row_mask:0xf bank_mask:0xf
	s_nop 1
	v_add_f32_dpp v72, v72, v72 row_bcast:15 row_mask:0xa bank_mask:0xf
	s_nop 1
	v_add_f32_dpp v72, v72, v72 row_bcast:31 row_mask:0xc bank_mask:0xf
	s_nop 1
	v_readlane_b32 s3, v72, 63
	s_nop 1
	v_mov_b32_e32 v72, s3
	v_fmamk_f32 v72, v72, 0x3a800000, v172
	v_rsq_f32_e32 v72, v72
	s_nop 0
	v_mul_f32_e32 v20, v20, v72
	v_mul_f32_e32 v21, v21, v72
	v_mul_f32_e32 v22, v22, v72
	v_mul_f32_e32 v23, v23, v72
	v_mul_f32_e32 v20, v4, v20
	v_mul_f32_e32 v21, v5, v21
	v_mul_f32_e32 v22, v6, v22
	v_mul_f32_e32 v23, v7, v23
	v_cvt_pk_bf16_f32 v74, v20, v21
	v_cvt_pk_bf16_f32 v75, v22, v23
	global_store_dwordx2 v71, v[74:75], s[36:37]
	v_mul_f32_e32 v24, v24, v72
	v_mul_f32_e32 v25, v25, v72
	v_mul_f32_e32 v26, v26, v72
	v_mul_f32_e32 v27, v27, v72
	v_mul_f32_e32 v24, v8, v24
	v_mul_f32_e32 v25, v9, v25
	v_mul_f32_e32 v26, v10, v26
	v_mul_f32_e32 v27, v11, v27
	v_cvt_pk_bf16_f32 v76, v24, v25
	v_cvt_pk_bf16_f32 v77, v26, v27
	global_store_dwordx2 v71, v[76:77], s[36:37] offset:512
	v_mul_f32_e32 v28, v28, v72
	v_mul_f32_e32 v29, v29, v72
	v_mul_f32_e32 v30, v30, v72
	v_mul_f32_e32 v31, v31, v72
	v_mul_f32_e32 v28, v12, v28
	v_mul_f32_e32 v29, v13, v29
	v_mul_f32_e32 v30, v14, v30
	v_mul_f32_e32 v31, v15, v31
	v_cvt_pk_bf16_f32 v78, v28, v29
	v_cvt_pk_bf16_f32 v79, v30, v31
	global_store_dwordx2 v71, v[78:79], s[36:37] offset:1024
	v_mul_f32_e32 v32, v32, v72
	v_mul_f32_e32 v33, v33, v72
	v_mul_f32_e32 v34, v34, v72
	v_mul_f32_e32 v35, v35, v72
	v_mul_f32_e32 v32, v16, v32
	v_mul_f32_e32 v33, v17, v33
	v_mul_f32_e32 v34, v18, v34
	v_mul_f32_e32 v35, v19, v35
	v_cvt_pk_bf16_f32 v80, v32, v33
	v_cvt_pk_bf16_f32 v81, v34, v35
	global_store_dwordx2 v71, v[80:81], s[36:37] offset:1536
	s_add_u32 s36, s36, 0x400000
	s_addc_u32 s37, s37, 0
	global_load_dwordx4 v[20:23], v70, s[34:35]
	global_load_dwordx4 v[24:27], v70, s[34:35] offset:1024
	global_load_dwordx4 v[28:31], v70, s[34:35] offset:2048
	global_load_dwordx4 v[32:35], v70, s[34:35] offset:3072
	s_add_u32 s34, s34, 0x800000
	s_addc_u32 s35, s35, 0
	s_waitcnt vmcnt(16)
	v_mul_f32_e32 v72, v36, v36
	v_mul_f32_e32 v73, v37, v37
	v_fmac_f32_e32 v72, v38, v38
	v_fmac_f32_e32 v73, v39, v39
	v_fmac_f32_e32 v72, v40, v40
	v_fmac_f32_e32 v73, v41, v41
	v_fmac_f32_e32 v72, v42, v42
	v_fmac_f32_e32 v73, v43, v43
	v_fmac_f32_e32 v72, v44, v44
	v_fmac_f32_e32 v73, v45, v45
	v_fmac_f32_e32 v72, v46, v46
	v_fmac_f32_e32 v73, v47, v47
	v_fmac_f32_e32 v72, v48, v48
	v_fmac_f32_e32 v73, v49, v49
	v_fmac_f32_e32 v72, v50, v50
	v_fmac_f32_e32 v73, v51, v51
	v_add_f32_e32 v72, v72, v73
	s_nop 1
	v_add_f32_dpp v72, v72, v72 quad_perm:[1,0,3,2] row_mask:0xf bank_mask:0xf
	s_nop 1
	v_add_f32_dpp v72, v72, v72 quad_perm:[2,3,0,1] row_mask:0xf bank_mask:0xf
	s_nop 1
	v_add_f32_dpp v72, v72, v72 row_half_mirror row_mask:0xf bank_mask:0xf
	s_nop 1
	v_add_f32_dpp v72, v72, v72 row_mirror row_mask:0xf bank_mask:0xf
	s_nop 1
	v_add_f32_dpp v72, v72, v72 row_bcast:15 row_mask:0xa bank_mask:0xf
	s_nop 1
	v_add_f32_dpp v72, v72, v72 row_bcast:31 row_mask:0xc bank_mask:0xf
	s_nop 1
	v_readlane_b32 s3, v72, 63
	s_nop 1
	v_mov_b32_e32 v72, s3
	v_fmamk_f32 v72, v72, 0x3a800000, v172
	v_rsq_f32_e32 v72, v72
	s_nop 0
	v_mul_f32_e32 v36, v36, v72
	v_mul_f32_e32 v37, v37, v72
	v_mul_f32_e32 v38, v38, v72
	v_mul_f32_e32 v39, v39, v72
	v_mul_f32_e32 v36, v4, v36
	v_mul_f32_e32 v37, v5, v37
	v_mul_f32_e32 v38, v6, v38
	v_mul_f32_e32 v39, v7, v39
	v_cvt_pk_bf16_f32 v74, v36, v37
	v_cvt_pk_bf16_f32 v75, v38, v39
	global_store_dwordx2 v71, v[74:75], s[36:37]
	v_mul_f32_e32 v40, v40, v72
	v_mul_f32_e32 v41, v41, v72
	v_mul_f32_e32 v42, v42, v72
	v_mul_f32_e32 v43, v43, v72
	v_mul_f32_e32 v40, v8, v40
	v_mul_f32_e32 v41, v9, v41
	v_mul_f32_e32 v42, v10, v42
	v_mul_f32_e32 v43, v11, v43
	v_cvt_pk_bf16_f32 v76, v40, v41
	v_cvt_pk_bf16_f32 v77, v42, v43
	global_store_dwordx2 v71, v[76:77], s[36:37] offset:512
	v_mul_f32_e32 v44, v44, v72
	v_mul_f32_e32 v45, v45, v72
	v_mul_f32_e32 v46, v46, v72
	v_mul_f32_e32 v47, v47, v72
	v_mul_f32_e32 v44, v12, v44
	v_mul_f32_e32 v45, v13, v45
	v_mul_f32_e32 v46, v14, v46
	v_mul_f32_e32 v47, v15, v47
	v_cvt_pk_bf16_f32 v78, v44, v45
	v_cvt_pk_bf16_f32 v79, v46, v47
	global_store_dwordx2 v71, v[78:79], s[36:37] offset:1024
	v_mul_f32_e32 v48, v48, v72
	v_mul_f32_e32 v49, v49, v72
	v_mul_f32_e32 v50, v50, v72
	v_mul_f32_e32 v51, v51, v72
	v_mul_f32_e32 v48, v16, v48
	v_mul_f32_e32 v49, v17, v49
	v_mul_f32_e32 v50, v18, v50
	v_mul_f32_e32 v51, v19, v51
	v_cvt_pk_bf16_f32 v80, v48, v49
	v_cvt_pk_bf16_f32 v81, v50, v51
	global_store_dwordx2 v71, v[80:81], s[36:37] offset:1536
	s_add_u32 s36, s36, 0x400000
	s_addc_u32 s37, s37, 0
	global_load_dwordx4 v[36:39], v70, s[34:35]
	global_load_dwordx4 v[40:43], v70, s[34:35] offset:1024
	global_load_dwordx4 v[44:47], v70, s[34:35] offset:2048
	global_load_dwordx4 v[48:51], v70, s[34:35] offset:3072
	s_add_u32 s34, s34, 0x800000
	s_addc_u32 s35, s35, 0
	s_waitcnt vmcnt(16)
	v_mul_f32_e32 v72, v52, v52
	v_mul_f32_e32 v73, v53, v53
	v_fmac_f32_e32 v72, v54, v54
	v_fmac_f32_e32 v73, v55, v55
	v_fmac_f32_e32 v72, v56, v56
	v_fmac_f32_e32 v73, v57, v57
	v_fmac_f32_e32 v72, v58, v58
	v_fmac_f32_e32 v73, v59, v59
	v_fmac_f32_e32 v72, v60, v60
	v_fmac_f32_e32 v73, v61, v61
	v_fmac_f32_e32 v72, v62, v62
	v_fmac_f32_e32 v73, v63, v63
	v_fmac_f32_e32 v72, v64, v64
	v_fmac_f32_e32 v73, v65, v65
	v_fmac_f32_e32 v72, v66, v66
	v_fmac_f32_e32 v73, v67, v67
	v_add_f32_e32 v72, v72, v73
	s_nop 1
	v_add_f32_dpp v72, v72, v72 quad_perm:[1,0,3,2] row_mask:0xf bank_mask:0xf
	s_nop 1
	v_add_f32_dpp v72, v72, v72 quad_perm:[2,3,0,1] row_mask:0xf bank_mask:0xf
	s_nop 1
	v_add_f32_dpp v72, v72, v72 row_half_mirror row_mask:0xf bank_mask:0xf
	s_nop 1
	v_add_f32_dpp v72, v72, v72 row_mirror row_mask:0xf bank_mask:0xf
	s_nop 1
	v_add_f32_dpp v72, v72, v72 row_bcast:15 row_mask:0xa bank_mask:0xf
	s_nop 1
	v_add_f32_dpp v72, v72, v72 row_bcast:31 row_mask:0xc bank_mask:0xf
	s_nop 1
	v_readlane_b32 s3, v72, 63
	s_nop 1
	v_mov_b32_e32 v72, s3
	v_fmamk_f32 v72, v72, 0x3a800000, v172
	v_rsq_f32_e32 v72, v72
	s_nop 0
	v_mul_f32_e32 v52, v52, v72
	v_mul_f32_e32 v53, v53, v72
	v_mul_f32_e32 v54, v54, v72
	v_mul_f32_e32 v55, v55, v72
	v_mul_f32_e32 v52, v4, v52
	v_mul_f32_e32 v53, v5, v53
	v_mul_f32_e32 v54, v6, v54
	v_mul_f32_e32 v55, v7, v55
	v_cvt_pk_bf16_f32 v74, v52, v53
	v_cvt_pk_bf16_f32 v75, v54, v55
	global_store_dwordx2 v71, v[74:75], s[36:37]
	v_mul_f32_e32 v56, v56, v72
	v_mul_f32_e32 v57, v57, v72
	v_mul_f32_e32 v58, v58, v72
	v_mul_f32_e32 v59, v59, v72
	v_mul_f32_e32 v56, v8, v56
	v_mul_f32_e32 v57, v9, v57
	v_mul_f32_e32 v58, v10, v58
	v_mul_f32_e32 v59, v11, v59
	v_cvt_pk_bf16_f32 v76, v56, v57
	v_cvt_pk_bf16_f32 v77, v58, v59
	global_store_dwordx2 v71, v[76:77], s[36:37] offset:512
	v_mul_f32_e32 v60, v60, v72
	v_mul_f32_e32 v61, v61, v72
	v_mul_f32_e32 v62, v62, v72
	v_mul_f32_e32 v63, v63, v72
	v_mul_f32_e32 v60, v12, v60
	v_mul_f32_e32 v61, v13, v61
	v_mul_f32_e32 v62, v14, v62
	v_mul_f32_e32 v63, v15, v63
	v_cvt_pk_bf16_f32 v78, v60, v61
	v_cvt_pk_bf16_f32 v79, v62, v63
	global_store_dwordx2 v71, v[78:79], s[36:37] offset:1024
	v_mul_f32_e32 v64, v64, v72
	v_mul_f32_e32 v65, v65, v72
	v_mul_f32_e32 v66, v66, v72
	v_mul_f32_e32 v67, v67, v72
	v_mul_f32_e32 v64, v16, v64
	v_mul_f32_e32 v65, v17, v65
	v_mul_f32_e32 v66, v18, v66
	v_mul_f32_e32 v67, v19, v67
	v_cvt_pk_bf16_f32 v80, v64, v65
	v_cvt_pk_bf16_f32 v81, v66, v67
	global_store_dwordx2 v71, v[80:81], s[36:37] offset:1536
	s_add_u32 s36, s36, 0x400000
	s_addc_u32 s37, s37, 0
	s_cmpk_lt_u32 s0, 0x100
	s_cbranch_scc0 .Lnrm_ffn_nol8
	global_load_dwordx4 v[52:55], v70, s[34:35]
	global_load_dwordx4 v[56:59], v70, s[34:35] offset:1024
	global_load_dwordx4 v[60:63], v70, s[34:35] offset:2048
	global_load_dwordx4 v[64:67], v70, s[34:35] offset:3072
	s_add_u32 s34, s34, 0x800000
	s_addc_u32 s35, s35, 0

.LBB0_2484:
	s_or_b64 exec, exec, s[0:1]
	s_mov_b64 s[6:7], s[84:85]
	v_mov_b32_e32 v0, v196
	s_waitcnt lgkmcnt(0)
	v_mov_b32_e32 v2, v196
	s_barrier
	v_readlane_b32 s0, v249, 1
	s_nop 0
	s_cmpk_lg_u32 s0, 0x200
	s_cbranch_scc1 .Lnrm_ple_orig
	v_readlane_b32 s0, v249, 5
	v_lshrrev_b32_e32 v68, 6, v196
	s_load_dwordx4 s[28:31], s[84:85], 0x130
	s_load_dwordx2 s[32:33], s[84:85], 0xc0
	v_and_b32_e32 v69, 63, v196
	v_readfirstlane_b32 s1, v68
	v_lshlrev_b32_e32 v70, 4, v69
	v_lshlrev_b32_e32 v71, 3, v69
	s_add_i32 s0, s0, s1
	s_lshr_b32 s2, s0, 2
	s_and_b32 s3, s2, 7
	s_lshr_b32 s2, s2, 3
	s_lshl_b32 s2, s2, 2
	s_add_i32 s2, s2, s1
	s_lshl_b32 s0, s3, 7
	s_and_b32 s3, s2, 0x7f
	s_add_i32 s0, s0, s3
	s_lshr_b32 s2, s2, 7
	s_lshl_b32 s2, s2, 10
	s_add_i32 s0, s0, s2
	s_waitcnt lgkmcnt(0)
	s_lshl_b32 s2, s72, 2
	s_add_u32 s32, s32, s2
	s_addc_u32 s33, s33, 0
	global_load_dwordx4 v[4:7], v70, s[32:33]
	global_load_dwordx4 v[8:11], v70, s[32:33] offset:1024
	global_load_dwordx4 v[12:15], v70, s[32:33] offset:2048
	global_load_dwordx4 v[16:19], v70, s[32:33] offset:3072
	s_lshl_b32 s2, s0, 12
	s_add_u32 s34, s28, s2
	s_addc_u32 s35, s29, 0
	s_lshl_b32 s2, s0, 11
	s_add_u32 s36, s30, s2
	s_addc_u32 s37, s31, 0
	global_load_dwordx4 v[20:23], v70, s[34:35]
	global_load_dwordx4 v[24:27], v70, s[34:35] offset:1024
	global_load_dwordx4 v[28:31], v70, s[34:35] offset:2048
	global_load_dwordx4 v[32:35], v70, s[34:35] offset:3072
	s_add_u32 s34, s34, 0x800000
	s_addc_u32 s35, s35, 0
	global_load_dwordx4 v[36:39], v70, s[34:35]
	global_load_dwordx4 v[40:43], v70, s[34:35] offset:1024
	global_load_dwordx4 v[44:47], v70, s[34:35] offset:2048
	global_load_dwordx4 v[48:51], v70, s[34:35] offset:3072
	s_add_u32 s34, s34, 0x800000
	s_addc_u32 s35, s35, 0
	global_load_dwordx4 v[52:55], v70, s[34:35]
	global_load_dwordx4 v[56:59], v70, s[34:35] offset:1024
	global_load_dwordx4 v[60:63], v70, s[34:35] offset:2048
	global_load_dwordx4 v[64:67], v70, s[34:35] offset:3072
	s_add_u32 s34, s34, 0x800000
	s_addc_u32 s35, s35, 0
	s_waitcnt vmcnt(8)
	v_mul_f32_e32 v72, v20, v20
	v_mul_f32_e32 v73, v21, v21
	v_fmac_f32_e32 v72, v22, v22
	v_fmac_f32_e32 v73, v23, v23
	v_fmac_f32_e32 v72, v24, v24
	v_fmac_f32_e32 v73, v25, v25
	v_fmac_f32_e32 v72, v26, v26
	v_fmac_f32_e32 v73, v27, v27
	v_fmac_f32_e32 v72, v28, v28
	v_fmac_f32_e32 v73, v29, v29
	v_fmac_f32_e32 v72, v30, v30
	v_fmac_f32_e32 v73, v31, v31
	v_fmac_f32_e32 v72, v32, v32
	v_fmac_f32_e32 v73, v33, v33
	v_fmac_f32_e32 v72, v34, v34
	v_fmac_f32_e32 v73, v35, v35
	v_add_f32_e32 v72, v72, v73
	s_nop 1
	v_add_f32_dpp v72, v72, v72 quad_perm:[1,0,3,2] row_mask:0xf bank_mask:0xf
	s_nop 1
	v_add_f32_dpp v72, v72, v72 quad_perm:[2,3,0,1] row_mask:0xf bank_mask:0xf
	s_nop 1
	v_add_f32_dpp v72, v72, v72 row_half_mirror row_mask:0xf bank_mask:0xf
	s_nop 1
	v_add_f32_dpp v72, v72, v72 row_mirror row_mask:0xf bank_mask:0xf
	s_nop 1
	v_add_f32_dpp v72, v72, v72 row_bcast:15 row_mask:0xa bank_mask:0xf
	s_nop 1
	v_add_f32_dpp v72, v72, v72 row_bcast:31 row_mask:0xc bank_mask:0xf
	s_nop 1
	v_readlane_b32 s3, v72, 63
	s_nop 1
	v_mov_b32_e32 v72, s3
	v_fmamk_f32 v72, v72, 0x3a800000, v172
	v_rsq_f32_e32 v72, v72
	s_nop 0
	v_mul_f32_e32 v20, v20, v72
	v_mul_f32_e32 v21, v21, v72
	v_mul_f32_e32 v22, v22, v72
	v_mul_f32_e32 v23, v23, v72
	v_mul_f32_e32 v20, v4, v20
	v_mul_f32_e32 v21, v5, v21
	v_mul_f32_e32 v22, v6, v22
	v_mul_f32_e32 v23, v7, v23
	v_cvt_pk_bf16_f32 v74, v20, v21
	v_cvt_pk_bf16_f32 v75, v22, v23
	global_store_dwordx2 v71, v[74:75], s[36:37]
	v_mul_f32_e32 v24, v24, v72
	v_mul_f32_e32 v25, v25, v72
	v_mul_f32_e32 v26, v26, v72
	v_mul_f32_e32 v27, v27, v72
	v_mul_f32_e32 v24, v8, v24
	v_mul_f32_e32 v25, v9, v25
	v_mul_f32_e32 v26, v10, v26
	v_mul_f32_e32 v27, v11, v27
	v_cvt_pk_bf16_f32 v76, v24, v25
	v_cvt_pk_bf16_f32 v77, v26, v27
	global_store_dwordx2 v71, v[76:77], s[36:37] offset:512
	v_mul_f32_e32 v28, v28, v72
	v_mul_f32_e32 v29, v29, v72
	v_mul_f32_e32 v30, v30, v72
	v_mul_f32_e32 v31, v31, v72
	v_mul_f32_e32 v28, v12, v28
	v_mul_f32_e32 v29, v13, v29
	v_mul_f32_e32 v30, v14, v30
	v_mul_f32_e32 v31, v15, v31
	v_cvt_pk_bf16_f32 v78, v28, v29
	v_cvt_pk_bf16_f32 v79, v30, v31
	global_store_dwordx2 v71, v[78:79], s[36:37] offset:1024
	v_mul_f32_e32 v32, v32, v72
	v_mul_f32_e32 v33, v33, v72
	v_mul_f32_e32 v34, v34, v72
	v_mul_f32_e32 v35, v35, v72
	v_mul_f32_e32 v32, v16, v32
	v_mul_f32_e32 v33, v17, v33
	v_mul_f32_e32 v34, v18, v34
	v_mul_f32_e32 v35, v19, v35
	v_cvt_pk_bf16_f32 v80, v32, v33
	v_cvt_pk_bf16_f32 v81, v34, v35
	global_store_dwordx2 v71, v[80:81], s[36:37] offset:1536
	s_add_u32 s36, s36, 0x400000
	s_addc_u32 s37, s37, 0
	global_load_dwordx4 v[20:23], v70, s[34:35]
	global_load_dwordx4 v[24:27], v70, s[34:35] offset:1024
	global_load_dwordx4 v[28:31], v70, s[34:35] offset:2048
	global_load_dwordx4 v[32:35], v70, s[34:35] offset:3072
	s_add_u32 s34, s34, 0x800000
	s_addc_u32 s35, s35, 0
	s_waitcnt vmcnt(12)
	v_mul_f32_e32 v72, v36, v36
	v_mul_f32_e32 v73, v37, v37
	v_fmac_f32_e32 v72, v38, v38
	v_fmac_f32_e32 v73, v39, v39
	v_fmac_f32_e32 v72, v40, v40
	v_fmac_f32_e32 v73, v41, v41
	v_fmac_f32_e32 v72, v42, v42
	v_fmac_f32_e32 v73, v43, v43
	v_fmac_f32_e32 v72, v44, v44
	v_fmac_f32_e32 v73, v45, v45
	v_fmac_f32_e32 v72, v46, v46
	v_fmac_f32_e32 v73, v47, v47
	v_fmac_f32_e32 v72, v48, v48
	v_fmac_f32_e32 v73, v49, v49
	v_fmac_f32_e32 v72, v50, v50
	v_fmac_f32_e32 v73, v51, v51
	v_add_f32_e32 v72, v72, v73
	s_nop 1
	v_add_f32_dpp v72, v72, v72 quad_perm:[1,0,3,2] row_mask:0xf bank_mask:0xf
	s_nop 1
	v_add_f32_dpp v72, v72, v72 quad_perm:[2,3,0,1] row_mask:0xf bank_mask:0xf
	s_nop 1
	v_add_f32_dpp v72, v72, v72 row_half_mirror row_mask:0xf bank_mask:0xf
	s_nop 1
	v_add_f32_dpp v72, v72, v72 row_mirror row_mask:0xf bank_mask:0xf
	s_nop 1
	v_add_f32_dpp v72, v72, v72 row_bcast:15 row_mask:0xa bank_mask:0xf
	s_nop 1
	v_add_f32_dpp v72, v72, v72 row_bcast:31 row_mask:0xc bank_mask:0xf
	s_nop 1
	v_readlane_b32 s3, v72, 63
	s_nop 1
	v_mov_b32_e32 v72, s3
	v_fmamk_f32 v72, v72, 0x3a800000, v172
	v_rsq_f32_e32 v72, v72
	s_nop 0
	v_mul_f32_e32 v36, v36, v72
	v_mul_f32_e32 v37, v37, v72
	v_mul_f32_e32 v38, v38, v72
	v_mul_f32_e32 v39, v39, v72
	v_mul_f32_e32 v36, v4, v36
	v_mul_f32_e32 v37, v5, v37
	v_mul_f32_e32 v38, v6, v38
	v_mul_f32_e32 v39, v7, v39
	v_cvt_pk_bf16_f32 v74, v36, v37
	v_cvt_pk_bf16_f32 v75, v38, v39
	global_store_dwordx2 v71, v[74:75], s[36:37]
	v_mul_f32_e32 v40, v40, v72
	v_mul_f32_e32 v41, v41, v72
	v_mul_f32_e32 v42, v42, v72
	v_mul_f32_e32 v43, v43, v72
	v_mul_f32_e32 v40, v8, v40
	v_mul_f32_e32 v41, v9, v41
	v_mul_f32_e32 v42, v10, v42
	v_mul_f32_e32 v43, v11, v43
	v_cvt_pk_bf16_f32 v76, v40, v41
	v_cvt_pk_bf16_f32 v77, v42, v43
	global_store_dwordx2 v71, v[76:77], s[36:37] offset:512
	v_mul_f32_e32 v44, v44, v72
	v_mul_f32_e32 v45, v45, v72
	v_mul_f32_e32 v46, v46, v72
	v_mul_f32_e32 v47, v47, v72
	v_mul_f32_e32 v44, v12, v44
	v_mul_f32_e32 v45, v13, v45
	v_mul_f32_e32 v46, v14, v46
	v_mul_f32_e32 v47, v15, v47
	v_cvt_pk_bf16_f32 v78, v44, v45
	v_cvt_pk_bf16_f32 v79, v46, v47
	global_store_dwordx2 v71, v[78:79], s[36:37] offset:1024
	v_mul_f32_e32 v48, v48, v72
	v_mul_f32_e32 v49, v49, v72
	v_mul_f32_e32 v50, v50, v72
	v_mul_f32_e32 v51, v51, v72
	v_mul_f32_e32 v48, v16, v48
	v_mul_f32_e32 v49, v17, v49
	v_mul_f32_e32 v50, v18, v50
	v_mul_f32_e32 v51, v19, v51
	v_cvt_pk_bf16_f32 v80, v48, v49
	v_cvt_pk_bf16_f32 v81, v50, v51
	global_store_dwordx2 v71, v[80:81], s[36:37] offset:1536
	s_add_u32 s36, s36, 0x400000
	s_addc_u32 s37, s37, 0
	global_load_dwordx4 v[36:39], v70, s[34:35]
	global_load_dwordx4 v[40:43], v70, s[34:35] offset:1024
	global_load_dwordx4 v[44:47], v70, s[34:35] offset:2048
	global_load_dwordx4 v[48:51], v70, s[34:35] offset:3072
	s_add_u32 s34, s34, 0x800000
	s_addc_u32 s35, s35, 0
	s_waitcnt vmcnt(16)
	v_mul_f32_e32 v72, v52, v52
	v_mul_f32_e32 v73, v53, v53
	v_fmac_f32_e32 v72, v54, v54
	v_fmac_f32_e32 v73, v55, v55
	v_fmac_f32_e32 v72, v56, v56
	v_fmac_f32_e32 v73, v57, v57
	v_fmac_f32_e32 v72, v58, v58
	v_fmac_f32_e32 v73, v59, v59
	v_fmac_f32_e32 v72, v60, v60
	v_fmac_f32_e32 v73, v61, v61
	v_fmac_f32_e32 v72, v62, v62
	v_fmac_f32_e32 v73, v63, v63
	v_fmac_f32_e32 v72, v64, v64
	v_fmac_f32_e32 v73, v65, v65
	v_fmac_f32_e32 v72, v66, v66
	v_fmac_f32_e32 v73, v67, v67
	v_add_f32_e32 v72, v72, v73
	s_nop 1
	v_add_f32_dpp v72, v72, v72 quad_perm:[1,0,3,2] row_mask:0xf bank_mask:0xf
	s_nop 1
	v_add_f32_dpp v72, v72, v72 quad_perm:[2,3,0,1] row_mask:0xf bank_mask:0xf
	s_nop 1
	v_add_f32_dpp v72, v72, v72 row_half_mirror row_mask:0xf bank_mask:0xf
	s_nop 1
	v_add_f32_dpp v72, v72, v72 row_mirror row_mask:0xf bank_mask:0xf
	s_nop 1
	v_add_f32_dpp v72, v72, v72 row_bcast:15 row_mask:0xa bank_mask:0xf
	s_nop 1
	v_add_f32_dpp v72, v72, v72 row_bcast:31 row_mask:0xc bank_mask:0xf
	s_nop 1
	v_readlane_b32 s3, v72, 63
	s_nop 1
	v_mov_b32_e32 v72, s3
	v_fmamk_f32 v72, v72, 0x3a800000, v172
	v_rsq_f32_e32 v72, v72
	s_nop 0
	v_mul_f32_e32 v52, v52, v72
	v_mul_f32_e32 v53, v53, v72
	v_mul_f32_e32 v54, v54, v72
	v_mul_f32_e32 v55, v55, v72
	v_mul_f32_e32 v52, v4, v52
	v_mul_f32_e32 v53, v5, v53
	v_mul_f32_e32 v54, v6, v54
	v_mul_f32_e32 v55, v7, v55
	v_cvt_pk_bf16_f32 v74, v52, v53
	v_cvt_pk_bf16_f32 v75, v54, v55
	global_store_dwordx2 v71, v[74:75], s[36:37]
	v_mul_f32_e32 v56, v56, v72
	v_mul_f32_e32 v57, v57, v72
	v_mul_f32_e32 v58, v58, v72
	v_mul_f32_e32 v59, v59, v72
	v_mul_f32_e32 v56, v8, v56
	v_mul_f32_e32 v57, v9, v57
	v_mul_f32_e32 v58, v10, v58
	v_mul_f32_e32 v59, v11, v59
	v_cvt_pk_bf16_f32 v76, v56, v57
	v_cvt_pk_bf16_f32 v77, v58, v59
	global_store_dwordx2 v71, v[76:77], s[36:37] offset:512
	v_mul_f32_e32 v60, v60, v72
	v_mul_f32_e32 v61, v61, v72
	v_mul_f32_e32 v62, v62, v72
	v_mul_f32_e32 v63, v63, v72
	v_mul_f32_e32 v60, v12, v60
	v_mul_f32_e32 v61, v13, v61
	v_mul_f32_e32 v62, v14, v62
	v_mul_f32_e32 v63, v15, v63
	v_cvt_pk_bf16_f32 v78, v60, v61
	v_cvt_pk_bf16_f32 v79, v62, v63
	global_store_dwordx2 v71, v[78:79], s[36:37] offset:1024
	v_mul_f32_e32 v64, v64, v72
	v_mul_f32_e32 v65, v65, v72
	v_mul_f32_e32 v66, v66, v72
	v_mul_f32_e32 v67, v67, v72
	v_mul_f32_e32 v64, v16, v64
	v_mul_f32_e32 v65, v17, v65
	v_mul_f32_e32 v66, v18, v66
	v_mul_f32_e32 v67, v19, v67
	v_cvt_pk_bf16_f32 v80, v64, v65
	v_cvt_pk_bf16_f32 v81, v66, v67
	global_store_dwordx2 v71, v[80:81], s[36:37] offset:1536
	s_add_u32 s36, s36, 0x400000
	s_addc_u32 s37, s37, 0
	global_load_dwordx4 v[52:55], v70, s[34:35]
	global_load_dwordx4 v[56:59], v70, s[34:35] offset:1024
	global_load_dwordx4 v[60:63], v70, s[34:35] offset:2048
	global_load_dwordx4 v[64:67], v70, s[34:35] offset:3072
	s_add_u32 s34, s34, 0x800000
	s_addc_u32 s35, s35, 0
	s_waitcnt vmcnt(16)
	v_mul_f32_e32 v72, v20, v20
	v_mul_f32_e32 v73, v21, v21
	v_fmac_f32_e32 v72, v22, v22
	v_fmac_f32_e32 v73, v23, v23
	v_fmac_f32_e32 v72, v24, v24
	v_fmac_f32_e32 v73, v25, v25
	v_fmac_f32_e32 v72, v26, v26
	v_fmac_f32_e32 v73, v27, v27
	v_fmac_f32_e32 v72, v28, v28
	v_fmac_f32_e32 v73, v29, v29
	v_fmac_f32_e32 v72, v30, v30
	v_fmac_f32_e32 v73, v31, v31
	v_fmac_f32_e32 v72, v32, v32
	v_fmac_f32_e32 v73, v33, v33
	v_fmac_f32_e32 v72, v34, v34
	v_fmac_f32_e32 v73, v35, v35
	v_add_f32_e32 v72, v72, v73
	s_nop 1
	v_add_f32_dpp v72, v72, v72 quad_perm:[1,0,3,2] row_mask:0xf bank_mask:0xf
	s_nop 1
	v_add_f32_dpp v72, v72, v72 quad_perm:[2,3,0,1] row_mask:0xf bank_mask:0xf
	s_nop 1
	v_add_f32_dpp v72, v72, v72 row_half_mirror row_mask:0xf bank_mask:0xf
	s_nop 1
	v_add_f32_dpp v72, v72, v72 row_mirror row_mask:0xf bank_mask:0xf
	s_nop 1
	v_add_f32_dpp v72, v72, v72 row_bcast:15 row_mask:0xa bank_mask:0xf
	s_nop 1
	v_add_f32_dpp v72, v72, v72 row_bcast:31 row_mask:0xc bank_mask:0xf
	s_nop 1
	v_readlane_b32 s3, v72, 63
	s_nop 1
	v_mov_b32_e32 v72, s3
	v_fmamk_f32 v72, v72, 0x3a800000, v172
	v_rsq_f32_e32 v72, v72
	s_nop 0
	v_mul_f32_e32 v20, v20, v72
	v_mul_f32_e32 v21, v21, v72
	v_mul_f32_e32 v22, v22, v72
	v_mul_f32_e32 v23, v23, v72
	v_mul_f32_e32 v20, v4, v20
	v_mul_f32_e32 v21, v5, v21
	v_mul_f32_e32 v22, v6, v22
	v_mul_f32_e32 v23, v7, v23
	v_cvt_pk_bf16_f32 v74, v20, v21
	v_cvt_pk_bf16_f32 v75, v22, v23
	global_store_dwordx2 v71, v[74:75], s[36:37]
	v_mul_f32_e32 v24, v24, v72
	v_mul_f32_e32 v25, v25, v72
	v_mul_f32_e32 v26, v26, v72
	v_mul_f32_e32 v27, v27, v72
	v_mul_f32_e32 v24, v8, v24
	v_mul_f32_e32 v25, v9, v25
	v_mul_f32_e32 v26, v10, v26
	v_mul_f32_e32 v27, v11, v27
	v_cvt_pk_bf16_f32 v76, v24, v25
	v_cvt_pk_bf16_f32 v77, v26, v27
	global_store_dwordx2 v71, v[76:77], s[36:37] offset:512
	v_mul_f32_e32 v28, v28, v72
	v_mul_f32_e32 v29, v29, v72
	v_mul_f32_e32 v30, v30, v72
	v_mul_f32_e32 v31, v31, v72
	v_mul_f32_e32 v28, v12, v28
	v_mul_f32_e32 v29, v13, v29
	v_mul_f32_e32 v30, v14, v30
	v_mul_f32_e32 v31, v15, v31
	v_cvt_pk_bf16_f32 v78, v28, v29
	v_cvt_pk_bf16_f32 v79, v30, v31
	global_store_dwordx2 v71, v[78:79], s[36:37] offset:1024
	v_mul_f32_e32 v32, v32, v72
	v_mul_f32_e32 v33, v33, v72
	v_mul_f32_e32 v34, v34, v72
	v_mul_f32_e32 v35, v35, v72
	v_mul_f32_e32 v32, v16, v32
	v_mul_f32_e32 v33, v17, v33
	v_mul_f32_e32 v34, v18, v34
	v_mul_f32_e32 v35, v19, v35
	v_cvt_pk_bf16_f32 v80, v32, v33
	v_cvt_pk_bf16_f32 v81, v34, v35
	global_store_dwordx2 v71, v[80:81], s[36:37] offset:1536
	s_add_u32 s36, s36, 0x400000
	s_addc_u32 s37, s37, 0
	global_load_dwordx4 v[20:23], v70, s[34:35]
	global_load_dwordx4 v[24:27], v70, s[34:35] offset:1024
	global_load_dwordx4 v[28:31], v70, s[34:35] offset:2048
	global_load_dwordx4 v[32:35], v70, s[34:35] offset:3072
	s_add_u32 s34, s34, 0x800000
	s_addc_u32 s35, s35, 0
	s_waitcnt vmcnt(16)
	v_mul_f32_e32 v72, v36, v36
	v_mul_f32_e32 v73, v37, v37
	v_fmac_f32_e32 v72, v38, v38
	v_fmac_f32_e32 v73, v39, v39
	v_fmac_f32_e32 v72, v40, v40
	v_fmac_f32_e32 v73, v41, v41
	v_fmac_f32_e32 v72, v42, v42
	v_fmac_f32_e32 v73, v43, v43
	v_fmac_f32_e32 v72, v44, v44
	v_fmac_f32_e32 v73, v45, v45
	v_fmac_f32_e32 v72, v46, v46
	v_fmac_f32_e32 v73, v47, v47
	v_fmac_f32_e32 v72, v48, v48
	v_fmac_f32_e32 v73, v49, v49
	v_fmac_f32_e32 v72, v50, v50
	v_fmac_f32_e32 v73, v51, v51
	v_add_f32_e32 v72, v72, v73
	s_nop 1
	v_add_f32_dpp v72, v72, v72 quad_perm:[1,0,3,2] row_mask:0xf bank_mask:0xf
	s_nop 1
	v_add_f32_dpp v72, v72, v72 quad_perm:[2,3,0,1] row_mask:0xf bank_mask:0xf
	s_nop 1
	v_add_f32_dpp v72, v72, v72 row_half_mirror row_mask:0xf bank_mask:0xf
	s_nop 1
	v_add_f32_dpp v72, v72, v72 row_mirror row_mask:0xf bank_mask:0xf
	s_nop 1
	v_add_f32_dpp v72, v72, v72 row_bcast:15 row_mask:0xa bank_mask:0xf
	s_nop 1
	v_add_f32_dpp v72, v72, v72 row_bcast:31 row_mask:0xc bank_mask:0xf
	s_nop 1
	v_readlane_b32 s3, v72, 63
	s_nop 1
	v_mov_b32_e32 v72, s3
	v_fmamk_f32 v72, v72, 0x3a800000, v172
	v_rsq_f32_e32 v72, v72
	s_nop 0
	v_mul_f32_e32 v36, v36, v72
	v_mul_f32_e32 v37, v37, v72
	v_mul_f32_e32 v38, v38, v72
	v_mul_f32_e32 v39, v39, v72
	v_mul_f32_e32 v36, v4, v36
	v_mul_f32_e32 v37, v5, v37
	v_mul_f32_e32 v38, v6, v38
	v_mul_f32_e32 v39, v7, v39
	v_cvt_pk_bf16_f32 v74, v36, v37
	v_cvt_pk_bf16_f32 v75, v38, v39
	global_store_dwordx2 v71, v[74:75], s[36:37]
	v_mul_f32_e32 v40, v40, v72
	v_mul_f32_e32 v41, v41, v72
	v_mul_f32_e32 v42, v42, v72
	v_mul_f32_e32 v43, v43, v72
	v_mul_f32_e32 v40, v8, v40
	v_mul_f32_e32 v41, v9, v41
	v_mul_f32_e32 v42, v10, v42
	v_mul_f32_e32 v43, v11, v43
	v_cvt_pk_bf16_f32 v76, v40, v41
	v_cvt_pk_bf16_f32 v77, v42, v43
	global_store_dwordx2 v71, v[76:77], s[36:37] offset:512
	v_mul_f32_e32 v44, v44, v72
	v_mul_f32_e32 v45, v45, v72
	v_mul_f32_e32 v46, v46, v72
	v_mul_f32_e32 v47, v47, v72
	v_mul_f32_e32 v44, v12, v44
	v_mul_f32_e32 v45, v13, v45
	v_mul_f32_e32 v46, v14, v46
	v_mul_f32_e32 v47, v15, v47
	v_cvt_pk_bf16_f32 v78, v44, v45
	v_cvt_pk_bf16_f32 v79, v46, v47
	global_store_dwordx2 v71, v[78:79], s[36:37] offset:1024
	v_mul_f32_e32 v48, v48, v72
	v_mul_f32_e32 v49, v49, v72
	v_mul_f32_e32 v50, v50, v72
	v_mul_f32_e32 v51, v51, v72
	v_mul_f32_e32 v48, v16, v48
	v_mul_f32_e32 v49, v17, v49
	v_mul_f32_e32 v50, v18, v50
	v_mul_f32_e32 v51, v19, v51
	v_cvt_pk_bf16_f32 v80, v48, v49
	v_cvt_pk_bf16_f32 v81, v50, v51
	global_store_dwordx2 v71, v[80:81], s[36:37] offset:1536
	s_add_u32 s36, s36, 0x400000
	s_addc_u32 s37, s37, 0
	global_load_dwordx4 v[36:39], v70, s[34:35]
	global_load_dwordx4 v[40:43], v70, s[34:35] offset:1024
	global_load_dwordx4 v[44:47], v70, s[34:35] offset:2048
	global_load_dwordx4 v[48:51], v70, s[34:35] offset:3072
	s_add_u32 s34, s34, 0x800000
	s_addc_u32 s35, s35, 0
	s_waitcnt vmcnt(16)
	v_mul_f32_e32 v72, v52, v52
	v_mul_f32_e32 v73, v53, v53
	v_fmac_f32_e32 v72, v54, v54
	v_fmac_f32_e32 v73, v55, v55
	v_fmac_f32_e32 v72, v56, v56
	v_fmac_f32_e32 v73, v57, v57
	v_fmac_f32_e32 v72, v58, v58
	v_fmac_f32_e32 v73, v59, v59
	v_fmac_f32_e32 v72, v60, v60
	v_fmac_f32_e32 v73, v61, v61
	v_fmac_f32_e32 v72, v62, v62
	v_fmac_f32_e32 v73, v63, v63
	v_fmac_f32_e32 v72, v64, v64
	v_fmac_f32_e32 v73, v65, v65
	v_fmac_f32_e32 v72, v66, v66
	v_fmac_f32_e32 v73, v67, v67
	v_add_f32_e32 v72, v72, v73
	s_nop 1
	v_add_f32_dpp v72, v72, v72 quad_perm:[1,0,3,2] row_mask:0xf bank_mask:0xf
	s_nop 1
	v_add_f32_dpp v72, v72, v72 quad_perm:[2,3,0,1] row_mask:0xf bank_mask:0xf
	s_nop 1
	v_add_f32_dpp v72, v72, v72 row_half_mirror row_mask:0xf bank_mask:0xf
	s_nop 1
	v_add_f32_dpp v72, v72, v72 row_mirror row_mask:0xf bank_mask:0xf
	s_nop 1
	v_add_f32_dpp v72, v72, v72 row_bcast:15 row_mask:0xa bank_mask:0xf
	s_nop 1
	v_add_f32_dpp v72, v72, v72 row_bcast:31 row_mask:0xc bank_mask:0xf
	s_nop 1
	v_readlane_b32 s3, v72, 63
	s_nop 1
	v_mov_b32_e32 v72, s3
	v_fmamk_f32 v72, v72, 0x3a800000, v172
	v_rsq_f32_e32 v72, v72
	s_nop 0
	v_mul_f32_e32 v52, v52, v72
	v_mul_f32_e32 v53, v53, v72
	v_mul_f32_e32 v54, v54, v72
	v_mul_f32_e32 v55, v55, v72
	v_mul_f32_e32 v52, v4, v52
	v_mul_f32_e32 v53, v5, v53
	v_mul_f32_e32 v54, v6, v54
	v_mul_f32_e32 v55, v7, v55
	v_cvt_pk_bf16_f32 v74, v52, v53
	v_cvt_pk_bf16_f32 v75, v54, v55
	global_store_dwordx2 v71, v[74:75], s[36:37]
	v_mul_f32_e32 v56, v56, v72
	v_mul_f32_e32 v57, v57, v72
	v_mul_f32_e32 v58, v58, v72
	v_mul_f32_e32 v59, v59, v72
	v_mul_f32_e32 v56, v8, v56
	v_mul_f32_e32 v57, v9, v57
	v_mul_f32_e32 v58, v10, v58
	v_mul_f32_e32 v59, v11, v59
	v_cvt_pk_bf16_f32 v76, v56, v57
	v_cvt_pk_bf16_f32 v77, v58, v59
	global_store_dwordx2 v71, v[76:77], s[36:37] offset:512
	v_mul_f32_e32 v60, v60, v72
	v_mul_f32_e32 v61, v61, v72
	v_mul_f32_e32 v62, v62, v72
	v_mul_f32_e32 v63, v63, v72
	v_mul_f32_e32 v60, v12, v60
	v_mul_f32_e32 v61, v13, v61
	v_mul_f32_e32 v62, v14, v62
	v_mul_f32_e32 v63, v15, v63
	v_cvt_pk_bf16_f32 v78, v60, v61
	v_cvt_pk_bf16_f32 v79, v62, v63
	global_store_dwordx2 v71, v[78:79], s[36:37] offset:1024
	v_mul_f32_e32 v64, v64, v72
	v_mul_f32_e32 v65, v65, v72
	v_mul_f32_e32 v66, v66, v72
	v_mul_f32_e32 v67, v67, v72
	v_mul_f32_e32 v64, v16, v64
	v_mul_f32_e32 v65, v17, v65
	v_mul_f32_e32 v66, v18, v66
	v_mul_f32_e32 v67, v19, v67
	v_cvt_pk_bf16_f32 v80, v64, v65
	v_cvt_pk_bf16_f32 v81, v66, v67
	global_store_dwordx2 v71, v[80:81], s[36:37] offset:1536
	s_add_u32 s36, s36, 0x400000
	s_addc_u32 s37, s37, 0
	s_cmpk_lt_u32 s0, 0x100
	s_cbranch_scc0 .Lnrm_ple_nol8
	global_load_dwordx4 v[52:55], v70, s[34:35]
	global_load_dwordx4 v[56:59], v70, s[34:35] offset:1024
	global_load_dwordx4 v[60:63], v70, s[34:35] offset:2048
	global_load_dwordx4 v[64:67], v70, s[34:35] offset:3072
	s_add_u32 s34, s34, 0x800000
	s_addc_u32 s35, s35, 0
